# baseline (speedup 1.0000x reference)
; #define LAS __attribute__((address_space(3)))
; __device__ __forceinline__ void attn_phase(LAS unsigned char* lds, bf16_t* Qb, const bf16_t* KVb, const bf16_t* GZ, const float* sinkp) {
;     ...
;                     {
;                         bf16x8 ka[4], kb[4], kc[4], kd[4];
; #pragma unroll
;                         for (int ks = 0; ks < 4; ++ks) { ka[ks] = *(const LAS bf16x8*)(Kc + kaddr[ks]); kb[ks] = *(const LAS bf16x8*)(Kc + kaddr[ks] + 8192); }
;                         __builtin_amdgcn_sched_barrier(0);
; #pragma unroll
;                         for (int ks = 0; ks < 4; ++ks) { kc[ks] = *(const LAS bf16x8*)(Kc + kaddr[4 + ks]); kd[ks] = *(const LAS bf16x8*)(Kc + kaddr[4 + ks] + 8192); }
;                         __builtin_amdgcn_sched_barrier(0);
; #pragma unroll
;                         for (int ks = 0; ks < 4; ++ks) { s0 = __builtin_amdgcn_mfma_f32_32x32x16_bf16(ka[ks], qf[ks], s0, 0, 0, 0); s1 = __builtin_amdgcn_mfma_f32_32x32x16_bf16(kb[ks], qf[ks], s1, 0, 0, 0); }
;                         __builtin_amdgcn_sched_barrier(0);
; #pragma unroll
;                         for (int ks = 0; ks < 4; ++ks) { s0 = __builtin_amdgcn_mfma_f32_32x32x16_bf16(kc[ks], qf[4 + ks], s0, 0, 0, 0); s1 = __builtin_amdgcn_mfma_f32_32x32x16_bf16(kd[ks], qf[4 + ks], s1, 0, 0, 0); }
;                         __builtin_amdgcn_sched_barrier(0);
;                     }
;                     if (needmask) {
;                         const int dqp = uq - (16 + bb * 128 + 64 * hf) + 128 - 4 * h;
; #pragma unroll
;                         for (int r = 0; r < 16; ++r) {
;                             const int c = (r & 3) + 8 * (r >> 2);
;                             s0[r] = ((unsigned)(dqp - c) <= 256u) ? s0[r] : NEG_INF; s1[r] = ((unsigned)(dqp - c - 32) <= 256u) ? s1[r] : NEG_INF;
;                         }
.LBB0_173:
	s_and_b64 vcc, exec, s[58:59]
	s_cbranch_vccz .LBB0_179
	s_and_b32 s3, s75, 0x8000
	s_add_i32 s3, s3, 0
	v_add_u32_e32 v68, s3, v150
	v_add_u32_e32 v72, s3, v151
	ds_read_b128 v[64:67], v68
	ds_read_b128 v[68:71], v68 offset:8192
	ds_read_b128 v[178:181], v72
	ds_read_b128 v[182:185], v72 offset:8192
	v_add_u32_e32 v72, s3, v152
	ds_read_b128 v[194:197], v72
	ds_read_b128 v[198:201], v72 offset:8192
	v_add_u32_e32 v72, s3, v153
	ds_read_b128 v[202:205], v72
	ds_read_b128 v[206:209], v72 offset:8192
	s_cmp_lg_u32 s77, s69
	s_cselect_b64 s[36:37], -1, 0
	v_add_u32_e32 v72, s3, v154
	ds_read_b128 v[210:213], v72
	ds_read_b128 v[214:217], v72 offset:8192
	v_add_u32_e32 v72, s3, v155
	ds_read_b128 v[218:221], v72
	ds_read_b128 v[238:241], v72 offset:8192
	v_add_u32_e32 v72, s3, v156
	ds_read_b128 v[242:245], v72
	ds_read_b128 v[246:249], v72 offset:8192
	v_add_u32_e32 v72, s3, v157
	ds_read_b128 v[250:253], v72
	ds_read_b128 v[228:231], v72 offset:8192
	s_waitcnt lgkmcnt(14)
	v_mfma_f32_32x32x16_bf16 v[80:95], v[64:67], v[112:115], 0
	v_mfma_f32_32x32x16_bf16 v[64:79], v[68:71], v[112:115], 0
	s_waitcnt lgkmcnt(13)
	v_mfma_f32_32x32x16_bf16 v[80:95], v[178:181], v[116:119], v[80:95]
	s_waitcnt lgkmcnt(12)
	v_mfma_f32_32x32x16_bf16 v[64:79], v[182:185], v[116:119], v[64:79]
	s_waitcnt lgkmcnt(11)
	v_mfma_f32_32x32x16_bf16 v[80:95], v[194:197], v[120:123], v[80:95]
	s_waitcnt lgkmcnt(10)
	v_mfma_f32_32x32x16_bf16 v[64:79], v[198:201], v[120:123], v[64:79]
	s_waitcnt lgkmcnt(9)
	v_mfma_f32_32x32x16_bf16 v[80:95], v[202:205], v[124:127], v[80:95]
	s_waitcnt lgkmcnt(8)
	v_mfma_f32_32x32x16_bf16 v[64:79], v[206:209], v[124:127], v[64:79]
	s_waitcnt lgkmcnt(7)
	v_mfma_f32_32x32x16_bf16 v[80:95], v[210:213], v[128:131], v[80:95]
	s_or_b64 s[36:37], s[4:5], s[36:37]
	s_waitcnt lgkmcnt(6)
	v_mfma_f32_32x32x16_bf16 v[64:79], v[214:217], v[128:131], v[64:79]
	s_waitcnt lgkmcnt(5)
	v_mfma_f32_32x32x16_bf16 v[80:95], v[218:221], v[132:135], v[80:95]
	s_waitcnt lgkmcnt(4)
	v_mfma_f32_32x32x16_bf16 v[64:79], v[238:241], v[132:135], v[64:79]
	s_waitcnt lgkmcnt(3)
	v_mfma_f32_32x32x16_bf16 v[80:95], v[242:245], v[136:139], v[80:95]
	s_waitcnt lgkmcnt(2)
	v_mfma_f32_32x32x16_bf16 v[64:79], v[246:249], v[136:139], v[64:79]
	s_waitcnt lgkmcnt(1)
	v_mfma_f32_32x32x16_bf16 v[80:95], v[250:253], v[140:143], v[80:95]
	s_waitcnt lgkmcnt(0)
	v_mfma_f32_32x32x16_bf16 v[64:79], v[228:231], v[140:143], v[64:79]
	s_andn2_b64 vcc, exec, s[36:37]
	s_cbranch_vccnz .LBB0_176
	s_lshl_b32 s36, s78, 6
	s_lshl_b32 s37, s77, 7
	s_or_b32 s36, s37, s36
	v_or_b32_e32 v177, s36, v160
	v_sub_u32_e32 v178, v175, v177
	s_cmp_lt_i32 s77, s69
	s_cbranch_scc0 .Lattn_mask_pos
	v_add_u32_e32 v178, 0xffffff00, v178
	v_cmp_ge_i32_e64 vcc, 0, v178
	v_cmp_ge_i32_e64 s[36:37], 32, v178
	v_cmp_ge_i32_e64 s[38:39], 1, v178
	v_cmp_ge_i32_e64 s[58:59], 33, v178
	s_nop 1
	v_cndmask_b32_e64 v80, v233, v80, vcc
	v_cndmask_b32_e64 v64, v233, v64, s[36:37]
	v_cndmask_b32_e64 v81, v233, v81, s[38:39]
	v_cndmask_b32_e64 v65, v233, v65, s[58:59]
	v_cmp_ge_i32_e64 vcc, 2, v178
	v_cmp_ge_i32_e64 s[36:37], 34, v178
	v_cmp_ge_i32_e64 s[38:39], 3, v178
	v_cmp_ge_i32_e64 s[58:59], 35, v178
	v_cndmask_b32_e64 v82, v233, v82, vcc
	v_cndmask_b32_e64 v66, v233, v66, s[36:37]
	v_cndmask_b32_e64 v83, v233, v83, s[38:39]
	v_cndmask_b32_e64 v67, v233, v67, s[58:59]
	v_cmp_ge_i32_e64 vcc, 8, v178
	v_cmp_ge_i32_e64 s[36:37], 40, v178
	v_cmp_ge_i32_e64 s[38:39], 9, v178
	v_cmp_ge_i32_e64 s[58:59], 41, v178
	v_cndmask_b32_e64 v84, v233, v84, vcc
	v_cndmask_b32_e64 v68, v233, v68, s[36:37]
	v_cndmask_b32_e64 v85, v233, v85, s[38:39]
	v_cndmask_b32_e64 v69, v233, v69, s[58:59]
	v_cmp_ge_i32_e64 vcc, 10, v178
	v_cmp_ge_i32_e64 s[36:37], 42, v178
	v_cmp_ge_i32_e64 s[38:39], 11, v178
	v_cmp_ge_i32_e64 s[58:59], 43, v178
	v_cndmask_b32_e64 v86, v233, v86, vcc
	v_cndmask_b32_e64 v70, v233, v70, s[36:37]
	v_cndmask_b32_e64 v87, v233, v87, s[38:39]
	v_cndmask_b32_e64 v71, v233, v71, s[58:59]
	v_cmp_ge_i32_e64 vcc, 16, v178
	v_cmp_ge_i32_e64 s[36:37], 48, v178
	v_cmp_ge_i32_e64 s[38:39], 17, v178
	v_cmp_ge_i32_e64 s[58:59], 49, v178
	v_cndmask_b32_e64 v88, v233, v88, vcc
	v_cndmask_b32_e64 v72, v233, v72, s[36:37]
	v_cndmask_b32_e64 v89, v233, v89, s[38:39]
	v_cndmask_b32_e64 v73, v233, v73, s[58:59]
	v_cmp_ge_i32_e64 vcc, 18, v178
	v_cmp_ge_i32_e64 s[36:37], 50, v178
	v_cmp_ge_i32_e64 s[38:39], 19, v178
	v_cmp_ge_i32_e64 s[58:59], 51, v178
	v_cndmask_b32_e64 v90, v233, v90, vcc
	v_cndmask_b32_e64 v74, v233, v74, s[36:37]
	v_cndmask_b32_e64 v91, v233, v91, s[38:39]
	v_cndmask_b32_e64 v75, v233, v75, s[58:59]
	v_cmp_ge_i32_e64 vcc, 24, v178
	v_cmp_ge_i32_e64 s[36:37], 56, v178
	v_cmp_ge_i32_e64 s[38:39], 25, v178
	v_cmp_ge_i32_e64 s[58:59], 57, v178
	v_cndmask_b32_e64 v92, v233, v92, vcc
	v_cndmask_b32_e64 v76, v233, v76, s[36:37]
	v_cndmask_b32_e64 v93, v233, v93, s[38:39]
	v_cndmask_b32_e64 v77, v233, v77, s[58:59]
	v_cmp_ge_i32_e64 vcc, 26, v178
	v_cmp_ge_i32_e64 s[36:37], 58, v178
	v_cmp_ge_i32_e64 s[38:39], 27, v178
	v_cmp_ge_i32_e64 s[58:59], 59, v178
	v_cndmask_b32_e64 v94, v233, v94, vcc
	v_cndmask_b32_e64 v78, v233, v78, s[36:37]
	v_cndmask_b32_e64 v95, v233, v95, s[38:39]
	v_cndmask_b32_e64 v79, v233, v79, s[58:59]
	s_branch .LBB0_176
; __device__ __forceinline__ void attn_phase(LAS unsigned char* lds, bf16_t* Qb, const bf16_t* KVb, const bf16_t* GZ, const float* sinkp) {
;     ...
;                     if (needmask) {
;                         const int dqp = uq - (16 + bb * 128 + 64 * hf) + 128 - 4 * h;
; #pragma unroll
;                         for (int r = 0; r < 16; ++r) {
;                             const int c = (r & 3) + 8 * (r >> 2);
;                             s0[r] = ((unsigned)(dqp - c) <= 256u) ? s0[r] : NEG_INF; s1[r] = ((unsigned)(dqp - c - 32) <= 256u) ? s1[r] : NEG_INF;
;                         }
.Lattn_mask_pos:
	v_cmp_le_i32_e64 vcc, 0, v178
	v_cmp_le_i32_e64 s[36:37], 32, v178
	v_cmp_le_i32_e64 s[38:39], 1, v178
	v_cmp_le_i32_e64 s[58:59], 33, v178
	s_nop 1
	v_cndmask_b32_e64 v80, v233, v80, vcc
	v_cndmask_b32_e64 v64, v233, v64, s[36:37]
	v_cndmask_b32_e64 v81, v233, v81, s[38:39]
	v_cndmask_b32_e64 v65, v233, v65, s[58:59]
	v_cmp_le_i32_e64 vcc, 2, v178
	v_cmp_le_i32_e64 s[36:37], 34, v178
	v_cmp_le_i32_e64 s[38:39], 3, v178
	v_cmp_le_i32_e64 s[58:59], 35, v178
	v_cndmask_b32_e64 v82, v233, v82, vcc
	v_cndmask_b32_e64 v66, v233, v66, s[36:37]
	v_cndmask_b32_e64 v83, v233, v83, s[38:39]
	v_cndmask_b32_e64 v67, v233, v67, s[58:59]
	v_cmp_le_i32_e64 vcc, 8, v178
	v_cmp_le_i32_e64 s[36:37], 40, v178
	v_cmp_le_i32_e64 s[38:39], 9, v178
	v_cmp_le_i32_e64 s[58:59], 41, v178
	v_cndmask_b32_e64 v84, v233, v84, vcc
	v_cndmask_b32_e64 v68, v233, v68, s[36:37]
	v_cndmask_b32_e64 v85, v233, v85, s[38:39]
	v_cndmask_b32_e64 v69, v233, v69, s[58:59]
	v_cmp_le_i32_e64 vcc, 10, v178
	v_cmp_le_i32_e64 s[36:37], 42, v178
	v_cmp_le_i32_e64 s[38:39], 11, v178
	v_cmp_le_i32_e64 s[58:59], 43, v178
	v_cndmask_b32_e64 v86, v233, v86, vcc
	v_cndmask_b32_e64 v70, v233, v70, s[36:37]
	v_cndmask_b32_e64 v87, v233, v87, s[38:39]
	v_cndmask_b32_e64 v71, v233, v71, s[58:59]
	v_cmp_le_i32_e64 vcc, 16, v178
	v_cmp_le_i32_e64 s[36:37], 48, v178
	v_cmp_le_i32_e64 s[38:39], 17, v178
	v_cmp_le_i32_e64 s[58:59], 49, v178
	v_cndmask_b32_e64 v88, v233, v88, vcc
	v_cndmask_b32_e64 v72, v233, v72, s[36:37]
	v_cndmask_b32_e64 v89, v233, v89, s[38:39]
	v_cndmask_b32_e64 v73, v233, v73, s[58:59]
	v_cmp_le_i32_e64 vcc, 18, v178
	v_cmp_le_i32_e64 s[36:37], 50, v178
	v_cmp_le_i32_e64 s[38:39], 19, v178
	v_cmp_le_i32_e64 s[58:59], 51, v178
	v_cndmask_b32_e64 v90, v233, v90, vcc
	v_cndmask_b32_e64 v74, v233, v74, s[36:37]
	v_cndmask_b32_e64 v91, v233, v91, s[38:39]
	v_cndmask_b32_e64 v75, v233, v75, s[58:59]
	v_cmp_le_i32_e64 vcc, 24, v178
	v_cmp_le_i32_e64 s[36:37], 56, v178
	v_cmp_le_i32_e64 s[38:39], 25, v178
	v_cmp_le_i32_e64 s[58:59], 57, v178
	v_cndmask_b32_e64 v92, v233, v92, vcc
	v_cndmask_b32_e64 v76, v233, v76, s[36:37]
	v_cndmask_b32_e64 v93, v233, v93, s[38:39]
	v_cndmask_b32_e64 v77, v233, v77, s[58:59]
	v_cmp_le_i32_e64 vcc, 26, v178
	v_cmp_le_i32_e64 s[36:37], 58, v178
	v_cmp_le_i32_e64 s[38:39], 27, v178
	v_cmp_le_i32_e64 s[58:59], 59, v178
	v_cndmask_b32_e64 v94, v233, v94, vcc
	v_cndmask_b32_e64 v78, v233, v78, s[36:37]
	v_cndmask_b32_e64 v95, v233, v95, s[38:39]
	v_cndmask_b32_e64 v79, v233, v79, s[58:59]
